# early L2 writeback by non-leader workgroups on arrival at each grid barrier
# baseline (speedup 1.0000x reference)
.LBB0_189:
	s_or_b64 exec, exec, s[28:29]
	v_cvt_f32_u32_e32 v4, v2
	s_waitcnt vmcnt(0)
	v_readfirstlane_b32 s3, v3
	v_sub_u32_e32 v3, 0, v2
	v_rcp_iflag_f32_e32 v4, v4
	v_add_u32_e32 v5, s3, v1
	v_mul_f32_e32 v4, 0x4f7ffffe, v4
	v_cvt_u32_f32_e32 v4, v4
	v_mul_lo_u32 v1, v3, v4
	v_mul_hi_u32 v1, v4, v1
	v_add_u32_e32 v1, v4, v1
	v_mul_hi_u32 v1, v5, v1
	v_mul_lo_u32 v3, v1, v2
	v_sub_u32_e32 v3, v5, v3
	v_add_u32_e32 v4, 1, v1
	v_cmp_ge_u32_e32 vcc, v3, v2
	s_nop 1
	v_cndmask_b32_e32 v1, v1, v4, vcc
	v_sub_u32_e32 v4, v3, v2
	v_cndmask_b32_e32 v3, v3, v4, vcc
	v_add_u32_e32 v4, 1, v1
	v_cmp_ge_u32_e32 vcc, v3, v2
	v_add_u32_e32 v3, 1, v5
	s_nop 0
	v_cndmask_b32_e32 v1, v1, v4, vcc
	v_mul_lo_u32 v4, v2, v1
	v_add_u32_e32 v2, v4, v2
	v_cmp_ne_u32_e32 vcc, v3, v2
	s_and_saveexec_b64 s[10:11], vcc
	s_xor_b64 s[10:11], exec, s[10:11]
	s_cbranch_execz .LBB0_203
	buffer_wbl2 sc1
	s_waitcnt lgkmcnt(0)
	v_mov_b32_e32 v0, 0x2000
	global_load_dword v0, v0, s[8:9] offset:1024 sc1
	s_add_u32 s58, s8, 0x2400
	s_addc_u32 s59, s9, 0
	s_waitcnt vmcnt(0)
	v_cmp_eq_u32_e32 vcc, v0, v1
	s_and_saveexec_b64 s[28:29], vcc
	s_cbranch_execz .LBB0_202
	s_add_u32 s34, s56, 0x13daa200
	s_addc_u32 s35, s57, 0
	s_mov_b32 s3, 1
	s_mov_b64 s[60:61], 0
	v_mov_b32_e32 v0, 0
	s_branch .LBB0_193

.LBB0_382:
	s_or_b64 exec, exec, s[10:11]
	v_cvt_f32_u32_e32 v4, v2
	s_waitcnt vmcnt(0)
	v_readfirstlane_b32 s3, v3
	v_sub_u32_e32 v3, 0, v2
	v_rcp_iflag_f32_e32 v4, v4
	v_add_u32_e32 v5, s3, v1
	v_mul_f32_e32 v4, 0x4f7ffffe, v4
	v_cvt_u32_f32_e32 v4, v4
	v_mul_lo_u32 v1, v3, v4
	v_mul_hi_u32 v1, v4, v1
	v_add_u32_e32 v1, v4, v1
	v_mul_hi_u32 v1, v5, v1
	v_mul_lo_u32 v3, v1, v2
	v_sub_u32_e32 v3, v5, v3
	v_add_u32_e32 v4, 1, v1
	v_cmp_ge_u32_e32 vcc, v3, v2
	s_nop 1
	v_cndmask_b32_e32 v1, v1, v4, vcc
	v_sub_u32_e32 v4, v3, v2
	v_cndmask_b32_e32 v3, v3, v4, vcc
	v_add_u32_e32 v4, 1, v1
	v_cmp_ge_u32_e32 vcc, v3, v2
	v_add_u32_e32 v3, 1, v5
	s_nop 0
	v_cndmask_b32_e32 v1, v1, v4, vcc
	v_mul_lo_u32 v4, v2, v1
	v_add_u32_e32 v2, v4, v2
	v_cmp_ne_u32_e32 vcc, v3, v2
	s_and_saveexec_b64 s[8:9], vcc
	s_xor_b64 s[8:9], exec, s[8:9]
	s_cbranch_execz .LBB0_396
	buffer_wbl2 sc1
	s_waitcnt lgkmcnt(0)
	v_mov_b32_e32 v0, 0x2000
	global_load_dword v0, v0, s[6:7] offset:1024 sc1
	s_add_u32 s22, s6, 0x2400
	s_addc_u32 s23, s7, 0
	s_waitcnt vmcnt(0)
	v_cmp_eq_u32_e32 vcc, v0, v1
	s_and_saveexec_b64 s[10:11], vcc
	s_cbranch_execz .LBB0_395
	s_add_u32 s20, s56, 0x13daa200
	s_addc_u32 s21, s57, 0
	s_mov_b32 s3, 1
	s_mov_b64 s[28:29], 0
	v_mov_b32_e32 v0, 0
	s_branch .LBB0_386

.LBB0_488:
	s_or_b64 exec, exec, s[16:17]
	v_cvt_f32_u32_e32 v4, v2
	s_waitcnt vmcnt(0)
	v_readfirstlane_b32 s3, v3
	v_sub_u32_e32 v3, 0, v2
	v_rcp_iflag_f32_e32 v4, v4
	v_add_u32_e32 v5, s3, v1
	v_mul_f32_e32 v4, 0x4f7ffffe, v4
	v_cvt_u32_f32_e32 v4, v4
	v_mul_lo_u32 v1, v3, v4
	v_mul_hi_u32 v1, v4, v1
	v_add_u32_e32 v1, v4, v1
	v_mul_hi_u32 v1, v5, v1
	v_mul_lo_u32 v3, v1, v2
	v_sub_u32_e32 v3, v5, v3
	v_add_u32_e32 v4, 1, v1
	v_cmp_ge_u32_e32 vcc, v3, v2
	s_nop 1
	v_cndmask_b32_e32 v1, v1, v4, vcc
	v_sub_u32_e32 v4, v3, v2
	v_cndmask_b32_e32 v3, v3, v4, vcc
	v_add_u32_e32 v4, 1, v1
	v_cmp_ge_u32_e32 vcc, v3, v2
	v_add_u32_e32 v3, 1, v5
	s_nop 0
	v_cndmask_b32_e32 v1, v1, v4, vcc
	v_mul_lo_u32 v4, v2, v1
	v_add_u32_e32 v2, v4, v2
	v_cmp_ne_u32_e32 vcc, v3, v2
	s_and_saveexec_b64 s[10:11], vcc
	s_xor_b64 s[10:11], exec, s[10:11]
	s_cbranch_execz .LBB0_502
	buffer_wbl2 sc1
	s_waitcnt lgkmcnt(0)
	v_mov_b32_e32 v0, 0x2000
	global_load_dword v0, v0, s[6:7] offset:1024 sc1
	s_add_u32 s20, s6, 0x2400
	s_addc_u32 s21, s7, 0
	s_waitcnt vmcnt(0)
	v_cmp_eq_u32_e32 vcc, v0, v1
	s_and_saveexec_b64 s[16:17], vcc
	s_cbranch_execz .LBB0_501
	s_add_u32 s18, s56, 0x13daa200
	s_addc_u32 s19, s57, 0
	s_mov_b32 s3, 1
	s_mov_b64 s[22:23], 0
	v_mov_b32_e32 v0, 0
	s_branch .LBB0_492

.LBB0_600:
	s_or_b64 exec, exec, s[10:11]
	v_cvt_f32_u32_e32 v4, v2
	s_waitcnt vmcnt(0)
	v_readfirstlane_b32 s3, v3
	v_sub_u32_e32 v3, 0, v2
	v_rcp_iflag_f32_e32 v4, v4
	v_add_u32_e32 v5, s3, v1
	v_mul_f32_e32 v4, 0x4f7ffffe, v4
	v_cvt_u32_f32_e32 v4, v4
	v_mul_lo_u32 v1, v3, v4
	v_mul_hi_u32 v1, v4, v1
	v_add_u32_e32 v1, v4, v1
	v_mul_hi_u32 v1, v5, v1
	v_mul_lo_u32 v3, v1, v2
	v_sub_u32_e32 v3, v5, v3
	v_add_u32_e32 v4, 1, v1
	v_cmp_ge_u32_e32 vcc, v3, v2
	s_nop 1
	v_cndmask_b32_e32 v1, v1, v4, vcc
	v_sub_u32_e32 v4, v3, v2
	v_cndmask_b32_e32 v3, v3, v4, vcc
	v_add_u32_e32 v4, 1, v1
	v_cmp_ge_u32_e32 vcc, v3, v2
	v_add_u32_e32 v3, 1, v5
	s_nop 0
	v_cndmask_b32_e32 v1, v1, v4, vcc
	v_mul_lo_u32 v4, v2, v1
	v_add_u32_e32 v2, v4, v2
	v_cmp_ne_u32_e32 vcc, v3, v2
	s_and_saveexec_b64 s[8:9], vcc
	s_xor_b64 s[8:9], exec, s[8:9]
	s_cbranch_execz .LBB0_614
	buffer_wbl2 sc1
	s_waitcnt lgkmcnt(0)
	v_mov_b32_e32 v0, 0x2000
	global_load_dword v0, v0, s[6:7] offset:1024 sc1
	s_add_u32 s18, s6, 0x2400
	s_addc_u32 s19, s7, 0
	s_waitcnt vmcnt(0)
	v_cmp_eq_u32_e32 vcc, v0, v1
	s_and_saveexec_b64 s[10:11], vcc
	s_cbranch_execz .LBB0_613
	s_add_u32 s16, s56, 0x13daa200
	s_addc_u32 s17, s57, 0
	s_mov_b32 s3, 1
	s_mov_b64 s[20:21], 0
	v_mov_b32_e32 v0, 0
	s_branch .LBB0_604

.LBB0_695:
	s_or_b64 exec, exec, s[10:11]
	v_cvt_f32_u32_e32 v4, v2
	s_waitcnt vmcnt(0)
	v_readfirstlane_b32 s3, v3
	v_sub_u32_e32 v3, 0, v2
	v_rcp_iflag_f32_e32 v4, v4
	v_add_u32_e32 v5, s3, v1
	v_mul_f32_e32 v4, 0x4f7ffffe, v4
	v_cvt_u32_f32_e32 v4, v4
	v_mul_lo_u32 v1, v3, v4
	v_mul_hi_u32 v1, v4, v1
	v_add_u32_e32 v1, v4, v1
	v_mul_hi_u32 v1, v5, v1
	v_mul_lo_u32 v3, v1, v2
	v_sub_u32_e32 v3, v5, v3
	v_add_u32_e32 v4, 1, v1
	v_cmp_ge_u32_e32 vcc, v3, v2
	s_nop 1
	v_cndmask_b32_e32 v1, v1, v4, vcc
	v_sub_u32_e32 v4, v3, v2
	v_cndmask_b32_e32 v3, v3, v4, vcc
	v_add_u32_e32 v4, 1, v1
	v_cmp_ge_u32_e32 vcc, v3, v2
	v_add_u32_e32 v3, 1, v5
	s_nop 0
	v_cndmask_b32_e32 v1, v1, v4, vcc
	v_mul_lo_u32 v4, v2, v1
	v_add_u32_e32 v2, v4, v2
	v_cmp_ne_u32_e32 vcc, v3, v2
	s_and_saveexec_b64 s[8:9], vcc
	s_xor_b64 s[8:9], exec, s[8:9]
	s_cbranch_execz .LBB0_709
	buffer_wbl2 sc1
	s_waitcnt lgkmcnt(0)
	v_mov_b32_e32 v0, 0x2000
	global_load_dword v0, v0, s[6:7] offset:1024 sc1
	s_add_u32 s16, s6, 0x2400
	s_addc_u32 s17, s7, 0
	s_waitcnt vmcnt(0)
	v_cmp_eq_u32_e32 vcc, v0, v1
	s_and_saveexec_b64 s[10:11], vcc
	s_cbranch_execz .LBB0_708
	s_add_u32 s12, s56, 0x13daa200
	s_addc_u32 s13, s57, 0
	s_mov_b32 s3, 1
	s_mov_b64 s[18:19], 0
	v_mov_b32_e32 v0, 0
	s_branch .LBB0_699
